# baseline (speedup 1.0000x reference)
; __device__ __forceinline__ void attn_prefetch(AttnPre& P, const bf16_t* proj, const float* cosT, const float* sinT, const AttnJob& J, int tid) {
;     ...
;     for (int it = 0; it < 5; ++it) { const int i = i0 + 64 * it, idx = idxk0 + i, tok = J.r + J.dil * idx; P.k[it] = (u32x4){0u, 0u, 0u, 0u}; P.v[it] = (u32x4){0u, 0u, 0u, 0u};
;         if (i < ANR && idx >= 0) { const bf16_t* rp = proj + (size_t)tok * LDP + 8 * c; P.k[it] = *(const u32x4*)(rp + J.kcol); P.v[it] = *(const u32x4*)(rp + J.vcol); } }
;     P.cs[0] = P.cs[1] = (f32x4){1.f, 1.f, 1.f, 1.f}; P.sn[0] = P.sn[1] = (f32x4){0.f, 0.f, 0.f, 0.f};
;     if (tid < 128 + ANR) { const int idx = tid < 128 ? idxq0 + tid : idxk0 + tid - 128;
;         if (idx >= 0) { const int tok = J.r + J.dil * idx; P.cs[0] = *(const f32x4*)(cosT + tok * 8); P.cs[1] = *(const f32x4*)(cosT + tok * 8 + 4); P.sn[0] = *(const f32x4*)(sinT + tok * 8); P.sn[1] = *(const f32x4*)(sinT + tok * 8 + 4); } }
.LBB0_205:
	s_or_b64 exec, exec, s[16:17]
	s_and_b64 s[16:17], s[28:29], exec
	s_cselect_b32 s20, 4, 16
	s_and_b64 s[16:17], s[30:31], exec
	s_mul_i32 s17, s37, 0xc00000
	s_cselect_b32 s20, 1, s20
	s_mul_hi_i32 s16, s37, 0xc00000
	s_add_u32 s28, s96, s17
	s_addc_u32 s29, s97, s16
	s_mul_hi_i32 s16, s37, 0x60000
	s_mul_i32 s37, s37, 0x60000
	s_add_u32 s30, s0, s37
	s_addc_u32 s31, s33, s16
	v_mov_b32_e32 v220, 0
	v_mov_b32_e32 v221, 0
	v_mov_b32_e32 v222, 0
	v_mov_b32_e32 v223, 0
	v_mov_b32_e32 v224, 0
	v_mov_b32_e32 v225, 0
	v_mov_b32_e32 v226, 0
	v_mov_b32_e32 v227, 0
	v_mov_b32_e32 v228, 1.0
	v_mov_b32_e32 v229, 1.0
	v_mov_b32_e32 v230, 1.0
	v_mov_b32_e32 v231, 1.0
	v_mov_b32_e32 v232, 1.0
	v_mov_b32_e32 v233, 1.0
	v_mov_b32_e32 v234, 1.0
	v_mov_b32_e32 v235, 1.0
	s_and_saveexec_b64 s[90:91], s[14:15]
	s_cbranch_execz .LBB0_209
	v_readlane_b32 s16, v252, 46
	v_add_u32_e32 v33, s74, v128
	v_add_u32_e32 v34, s59, v135
	v_readlane_b32 s17, v252, 47
	v_cndmask_b32_e64 v33, v34, v33, s[16:17]
	v_cmp_lt_i32_e32 vcc, -1, v33
	s_and_saveexec_b64 s[16:17], vcc
	s_cbranch_execz .LBB0_208
	v_lshlrev_b32_e32 v33, s35, v33
	v_add_lshl_u32 v34, v33, s22, 3
	v_ashrrev_i32_e32 v35, 31, v34
	v_readlane_b32 s74, v252, 44
	v_lshlrev_b64 v[34:35], 2, v[34:35]
	v_readlane_b32 s75, v252, 45
	s_nop 1
	v_lshl_add_u64 v[64:65], s[74:75], 0, v[34:35]
	v_readlane_b32 s74, v252, 40
	v_readlane_b32 s75, v252, 41
	global_load_dwordx4 v[220:223], v[64:65], off offset:16
	s_nop 0
	global_load_dwordx4 v[224:227], v[64:65], off
	v_lshl_add_u64 v[34:35], s[74:75], 0, v[34:35]
	global_load_dwordx4 v[228:231], v[34:35], off offset:16
	global_load_dwordx4 v[232:235], v[34:35], off

; __device__ __forceinline__ unsigned cvt_pk_bf16(float lo, float hi) { unsigned r; asm volatile("v_cvt_pk_bf16_f32 %0, %1, %2" : "=v"(r) : "v"(lo), "v"(hi)); return r; }
; #define LAS __attribute__((address_space(3)))
; __device__ __forceinline__ f32x4 mfma16(bf16x8 a, bf16x8 b, f32x4 c) { return __builtin_amdgcn_mfma_f32_16x16x32_bf16(a, b, c, 0, 0, 0); }
; __device__ __forceinline__ bf16x8 cat44(s16x4 lo, s16x4 hi) { return __builtin_shufflevector(lo, hi, 0, 1, 2, 3, 4, 5, 6, 7); }
; __device__ __forceinline__ s16x4 lds_tr(const LAS bf16_t* p) { return __builtin_bit_cast(s16x4, __builtin_amdgcn_ds_read_tr16_b64_v4i16((LAS v4i16_t*)p)); }
; __device__ __forceinline__ void attn_compute(LAS unsigned char* lds, const AttnJob& J, int tid) {
;     ...
;     float mx = NEG_BIG;
; #pragma unroll
;     for (int t = 1; t < 10; ++t) mx = fmaxf(mx, fmaxf(fmaxf(st[t][0], st[t][1]), fmaxf(st[t][2], st[t][3])));
;     mx = fmaxf(mx, __shfl_xor(mx, 16)); mx = fmaxf(mx, __shfl_xor(mx, 32));
;     if (J.has_sink) mx = fmaxf(mx, J.sink);
;     float den = 0.f;
; #pragma unroll
;     for (int t = 1; t < 10; ++t)
; #pragma unroll
;         for (int j = 0; j < 4; ++j) { const float p = __builtin_amdgcn_exp2f(st[t][j] - mx); st[t][j] = p; den += p; }
;     den += __shfl_xor(den, 16); den += __shfl_xor(den, 32);
;     if (J.has_sink) den += __builtin_amdgcn_exp2f(J.sink - mx);
;     f32x4 o[4];
; #pragma unroll
;     for (int dt = 0; dt < 4; ++dt) o[dt] = (f32x4){0.f, 0.f, 0.f, 0.f};
; #pragma unroll
;     for (int ks = 0; ks < 5; ++ks) {
;         u32x4 pw; pw.x = cvt_pk_bf16(st[2 * ks][0], st[2 * ks][1]); pw.y = cvt_pk_bf16(st[2 * ks][2], st[2 * ks][3]); pw.z = cvt_pk_bf16(st[2 * ks + 1][0], st[2 * ks + 1][1]); pw.w = cvt_pk_bf16(st[2 * ks + 1][2], st[2 * ks + 1][3]);
;         const bf16x8 pb = __builtin_bit_cast(bf16x8, pw);
; #pragma unroll
;         for (int dt = 0; dt < 4; ++dt) { const LAS bf16_t* vp = Vs + (16 * w + 32 * ks + quad * 4 + (l15 >> 2)) * AQP + 16 * dt + 4 * (l15 & 3);
;             const s16x4 lo = lds_tr(vp), hi = lds_tr(vp + 16 * AQP);
;             o[dt] = mfma16(cat44(lo, hi), pb, o[dt]); }
.LBB0_219:
	v_max_f32_e32 v33, v101, v101
	v_max_f32_e32 v34, v100, v100
	v_max_f32_e32 v33, v34, v33
	v_max_f32_e32 v34, v103, v103
	v_max_f32_e32 v35, v102, v102
	v_max_f32_e32 v34, v35, v34
	v_max3_f32 v33, v33, v34, s16
	v_max_f32_e32 v34, v95, v95
	v_max_f32_e32 v35, v94, v94
	v_max_f32_e32 v34, v35, v34
	v_max_f32_e32 v35, v91, v91
	v_max_f32_e32 v104, v90, v90
	v_max_f32_e32 v35, v104, v35
	v_max3_f32 v34, v92, v93, v34
	v_max3_f32 v35, v88, v89, v35
	v_max3_f32 v33, v33, v34, v35
	v_max_f32_e32 v34, v87, v87
	v_max_f32_e32 v35, v86, v86
	v_max_f32_e32 v34, v35, v34
	v_max_f32_e32 v35, v83, v83
	v_max_f32_e32 v104, v82, v82
	v_max_f32_e32 v35, v104, v35
	v_max3_f32 v34, v84, v85, v34
	v_max3_f32 v35, v80, v81, v35
	v_max3_f32 v33, v33, v34, v35
	v_max_f32_e32 v34, v79, v79
	v_max_f32_e32 v35, v78, v78
	v_max_f32_e32 v34, v35, v34
	v_max_f32_e32 v35, v71, v71
	v_max_f32_e32 v104, v70, v70
	v_max_f32_e32 v35, v104, v35
	v_max3_f32 v34, v76, v77, v34
	v_max3_f32 v35, v68, v69, v35
	v_max3_f32 v33, v33, v34, v35
	v_max_f32_e32 v34, v75, v75
	v_max_f32_e32 v35, v74, v74
	v_max_f32_e32 v34, v35, v34
	v_max_f32_e32 v35, v99, v99
	v_max_f32_e32 v104, v98, v98
	v_max_f32_e32 v35, v104, v35
	v_max3_f32 v34, v72, v73, v34
	v_max3_f32 v35, v96, v97, v35
	v_max3_f32 v33, v33, v34, v35
	ds_bpermute_b32 v34, v150, v33
	s_ashr_i32 s35, s34, 31
	s_cmp_lg_u64 s[24:25], 0
	s_waitcnt lgkmcnt(0)
	v_max_f32_e32 v34, v34, v34
	v_max_f32_e32 v33, v33, v34
	ds_bpermute_b32 v34, v151, v33
	s_waitcnt lgkmcnt(0)
	v_max_f32_e32 v34, v34, v34
	v_max_f32_e32 v33, v33, v34
	v_sub_f32_e32 v35, v101, v33
	v_exp_f32_e32 v101, v35
	v_sub_f32_e32 v35, v102, v33
	v_exp_f32_e32 v102, v35
	v_sub_f32_e32 v35, v103, v33
	v_exp_f32_e32 v103, v35
	v_sub_f32_e32 v35, v92, v33
	v_exp_f32_e32 v92, v35
	v_sub_f32_e32 v35, v93, v33
	v_exp_f32_e32 v93, v35
	v_sub_f32_e32 v35, v94, v33
	v_exp_f32_e32 v110, v35
	v_sub_f32_e32 v35, v95, v33
	v_exp_f32_e32 v111, v35
	v_sub_f32_e32 v35, v88, v33
	v_exp_f32_e32 v113, v35
	v_sub_f32_e32 v35, v89, v33
	v_exp_f32_e32 v119, v35
	v_sub_f32_e32 v35, v90, v33
	v_exp_f32_e32 v164, v35
	v_sub_f32_e32 v35, v91, v33
	v_exp_f32_e32 v165, v35
	v_sub_f32_e32 v35, v84, v33
	v_exp_f32_e32 v84, v35
	v_sub_f32_e32 v35, v85, v33
	v_exp_f32_e32 v85, v35
	v_sub_f32_e32 v35, v86, v33
	v_exp_f32_e32 v86, v35
	v_sub_f32_e32 v35, v87, v33
	v_exp_f32_e32 v87, v35
	v_sub_f32_e32 v35, v80, v33
	v_exp_f32_e32 v166, v35
	v_sub_f32_e32 v35, v81, v33
	v_exp_f32_e32 v167, v35
	v_sub_f32_e32 v35, v82, v33
	v_exp_f32_e32 v186, v35
	v_sub_f32_e32 v35, v83, v33
	v_exp_f32_e32 v187, v35
	v_sub_f32_e32 v35, v76, v33
	v_exp_f32_e32 v76, v35
	v_sub_f32_e32 v35, v77, v33
	v_sub_f32_e32 v34, v100, v33
	v_exp_f32_e32 v77, v35
	v_sub_f32_e32 v35, v78, v33
	v_exp_f32_e32 v100, v34
	v_exp_f32_e32 v78, v35
	v_sub_f32_e32 v35, v79, v33
	v_exp_f32_e32 v79, v35
	v_sub_f32_e32 v35, v68, v33
	v_exp_f32_e32 v80, v35
	v_sub_f32_e32 v35, v69, v33
	v_exp_f32_e32 v81, v35
	v_sub_f32_e32 v35, v70, v33
	v_add_f32_e32 v34, 0, v100
	v_exp_f32_e32 v82, v35
	v_sub_f32_e32 v35, v71, v33
	v_add_f32_e32 v34, v101, v34
	v_exp_f32_e32 v83, v35
	v_sub_f32_e32 v35, v72, v33
	v_sub_f32_e32 v68, v73, v33
	v_sub_f32_e32 v69, v74, v33
	v_sub_f32_e32 v71, v96, v33
	v_sub_f32_e32 v72, v97, v33
	v_sub_f32_e32 v73, v98, v33
	v_sub_f32_e32 v74, v99, v33
	v_cvt_pk_bf16_f32 v88, v32, v32
	v_cvt_pk_bf16_f32 v89, v32, v32
	v_cvt_pk_bf16_f32 v90, v100, v101
	v_cvt_pk_bf16_f32 v91, v102, v103
	ds_read_b64_tr_b16 v[96:97], v152 offset:59904
	ds_read_b64_tr_b16 v[94:95], v152 offset:57600
	ds_read_b64_tr_b16 v[98:99], v152 offset:57632
	ds_read_b64_tr_b16 v[100:101], v152 offset:59936
	v_add_f32_e32 v34, v102, v34
	v_add_f32_e32 v34, v103, v34
	ds_read_b64_tr_b16 v[102:103], v152 offset:57664
	ds_read_b64_tr_b16 v[104:105], v152 offset:59968
	ds_read_b64_tr_b16 v[106:107], v152 offset:57696
	ds_read_b64_tr_b16 v[108:109], v152 offset:60000
	v_add_f32_e32 v34, v92, v34
	v_add_f32_e32 v34, v93, v34
	s_waitcnt lgkmcnt(6)
	v_mfma_f32_16x16x32_bf16 v[94:97], v[94:97], v[88:91], 0
	v_add_f32_e32 v34, v110, v34
	v_add_f32_e32 v34, v111, v34
	v_add_f32_e32 v34, v113, v34
	s_waitcnt lgkmcnt(4)
	v_mfma_f32_16x16x32_bf16 v[98:101], v[98:101], v[88:91], 0
	v_add_f32_e32 v34, v119, v34
	v_add_f32_e32 v34, v164, v34
	v_add_f32_e32 v34, v165, v34
	s_waitcnt lgkmcnt(2)
	v_mfma_f32_16x16x32_bf16 v[102:105], v[102:105], v[88:91], 0
	v_add_f32_e32 v34, v84, v34
	v_add_f32_e32 v34, v85, v34
	v_add_f32_e32 v34, v86, v34
	s_waitcnt lgkmcnt(0)
	v_mfma_f32_16x16x32_bf16 v[88:91], v[106:109], v[88:91], 0
	v_cvt_pk_bf16_f32 v106, v92, v93
	v_cvt_pk_bf16_f32 v107, v110, v111
	v_cvt_pk_bf16_f32 v108, v113, v119
	v_cvt_pk_bf16_f32 v109, v164, v165
	ds_read_b64_tr_b16 v[184:185], v152 offset:64512
	ds_read_b64_tr_b16 v[182:183], v152 offset:62208
	ds_read_b64_tr_b16 v[92:93], v152 offset:62240
	s_waitcnt lgkmcnt(1)
	v_mfma_f32_16x16x32_bf16 v[182:185], v[182:185], v[106:109], v[94:97]
	s_nop 2
	ds_read_b64_tr_b16 v[94:95], v152 offset:64544
	v_add_f32_e32 v34, v87, v34
	v_add_f32_e32 v34, v166, v34
	s_waitcnt lgkmcnt(0)
	v_mfma_f32_16x16x32_bf16 v[92:95], v[92:95], v[106:109], v[98:101]
	ds_read_b64_tr_b16 v[96:97], v152 offset:62272
	s_nop 1
	ds_read_b64_tr_b16 v[98:99], v152 offset:64576
	v_add_f32_e32 v34, v167, v34
	v_add_f32_e32 v34, v186, v34
	s_waitcnt lgkmcnt(0)
	v_mfma_f32_16x16x32_bf16 v[96:99], v[96:99], v[106:109], v[102:105]
	ds_read_b64_tr_b16 v[100:101], v152 offset:62304
	s_nop 1
	ds_read_b64_tr_b16 v[102:103], v152 offset:64608
	v_cvt_pk_bf16_f32 v84, v84, v85
	v_cvt_pk_bf16_f32 v85, v86, v87
	s_waitcnt lgkmcnt(0)
; __device__ __forceinline__ unsigned cvt_pk_bf16(float lo, float hi) { unsigned r; asm volatile("v_cvt_pk_bf16_f32 %0, %1, %2" : "=v"(r) : "v"(lo), "v"(hi)); return r; }
; #define LAS __attribute__((address_space(3)))
; __device__ __forceinline__ f32x4 mfma16(bf16x8 a, bf16x8 b, f32x4 c) { return __builtin_amdgcn_mfma_f32_16x16x32_bf16(a, b, c, 0, 0, 0); }
; __device__ __forceinline__ bf16x8 cat44(s16x4 lo, s16x4 hi) { return __builtin_shufflevector(lo, hi, 0, 1, 2, 3, 4, 5, 6, 7); }
; __device__ __forceinline__ s16x4 lds_tr(const LAS bf16_t* p) { return __builtin_bit_cast(s16x4, __builtin_amdgcn_ds_read_tr16_b64_v4i16((LAS v4i16_t*)p)); }
; __device__ __forceinline__ void attn_compute(LAS unsigned char* lds, const AttnJob& J, int tid) {
;     ...
;     for (int ks = 0; ks < 5; ++ks) {
;         u32x4 pw; pw.x = cvt_pk_bf16(st[2 * ks][0], st[2 * ks][1]); pw.y = cvt_pk_bf16(st[2 * ks][2], st[2 * ks][3]); pw.z = cvt_pk_bf16(st[2 * ks + 1][0], st[2 * ks + 1][1]); pw.w = cvt_pk_bf16(st[2 * ks + 1][2], st[2 * ks + 1][3]);
;         const bf16x8 pb = __builtin_bit_cast(bf16x8, pw);
; #pragma unroll
;         for (int dt = 0; dt < 4; ++dt) { const LAS bf16_t* vp = Vs + (16 * w + 32 * ks + quad * 4 + (l15 >> 2)) * AQP + 16 * dt + 4 * (l15 & 3);
;             const s16x4 lo = lds_tr(vp), hi = lds_tr(vp + 16 * AQP);
;             o[dt] = mfma16(cat44(lo, hi), pb, o[dt]); }
;     }
;     const float inv = 1.0f / den;
;     const int tokq = J.r + J.dil * (idxq0 + 16 * w + l15);
;     bf16_t* op = J.out + (size_t)tokq * J.out_ld + J.out_col + quad * 4;
; #pragma unroll
;     for (int dt = 0; dt < 4; ++dt) { u32x2 wv; wv.x = cvt_pk_bf16(o[dt][0] * inv, o[dt][1] * inv); wv.y = cvt_pk_bf16(o[dt][2] * inv, o[dt][3] * inv); *(u32x2*)(op + 16 * dt) = wv; }
;     if (J.lse && quad == 0) J.lse[(size_t)tokq * 6 + J.lse_col] = (mx + __builtin_amdgcn_logf(den)) * 0.6931471805599453f;
	v_mfma_f32_16x16x32_bf16 v[88:91], v[100:103], v[106:109], v[88:91]
	v_cvt_pk_bf16_f32 v86, v166, v167
	v_cvt_pk_bf16_f32 v87, v186, v187
	ds_read_b64_tr_b16 v[102:103], v153 offset:11520
	ds_read_b64_tr_b16 v[100:101], v153 offset:9216
	ds_read_b64_tr_b16 v[104:105], v153 offset:9248
	ds_read_b64_tr_b16 v[106:107], v153 offset:11552
	s_waitcnt lgkmcnt(0)
	v_mfma_f32_16x16x32_bf16 v[92:95], v[104:107], v[84:87], v[92:95]
	ds_read_b64_tr_b16 v[104:105], v153 offset:9280
	ds_read_b64_tr_b16 v[106:107], v153 offset:11584
	v_add_f32_e32 v34, v187, v34
	v_add_f32_e32 v34, v76, v34
	v_add_f32_e32 v34, v77, v34
	v_add_f32_e32 v34, v78, v34
	v_add_f32_e32 v34, v79, v34
	s_waitcnt lgkmcnt(0)
	v_mfma_f32_16x16x32_bf16 v[96:99], v[104:107], v[84:87], v[96:99]
	ds_read_b64_tr_b16 v[104:105], v153 offset:9312
	ds_read_b64_tr_b16 v[106:107], v153 offset:11616
	v_add_f32_e32 v34, v80, v34
	v_exp_f32_e32 v35, v35
	v_add_f32_e32 v34, v81, v34
	v_exp_f32_e32 v68, v68
	v_add_f32_e32 v34, v82, v34
	v_exp_f32_e32 v69, v69
	v_sub_f32_e32 v70, v75, v33
	v_add_f32_e32 v34, v83, v34
	v_exp_f32_e32 v70, v70
	v_add_f32_e32 v34, v35, v34
	v_exp_f32_e32 v71, v71
	v_mfma_f32_16x16x32_bf16 v[100:103], v[100:103], v[84:87], v[182:185]
	v_cvt_pk_bf16_f32 v76, v76, v77
	v_cvt_pk_bf16_f32 v77, v78, v79
	v_cvt_pk_bf16_f32 v78, v80, v81
	s_waitcnt lgkmcnt(0)
	v_mfma_f32_16x16x32_bf16 v[84:87], v[104:107], v[84:87], v[88:91]
	v_cvt_pk_bf16_f32 v79, v82, v83
	ds_read_b64_tr_b16 v[82:83], v153 offset:16128
	ds_read_b64_tr_b16 v[80:81], v153 offset:13824
	s_nop 0
	ds_read_b64_tr_b16 v[88:89], v153 offset:13856
	ds_read_b64_tr_b16 v[90:91], v153 offset:16160
	v_add_f32_e32 v34, v68, v34
	v_exp_f32_e32 v72, v72
	v_add_f32_e32 v34, v69, v34
	v_exp_f32_e32 v73, v73
	v_add_f32_e32 v34, v70, v34
	v_exp_f32_e32 v74, v74
	v_add_f32_e32 v34, v71, v34
	v_add_f32_e32 v34, v72, v34
	v_add_f32_e32 v34, v73, v34
	v_add_f32_e32 v34, v74, v34
	ds_bpermute_b32 v75, v150, v34
	s_waitcnt lgkmcnt(1)
	v_mfma_f32_16x16x32_bf16 v[88:91], v[88:91], v[76:79], v[92:95]
	s_nop 2
	ds_read_b64_tr_b16 v[92:93], v153 offset:13888
	ds_read_b64_tr_b16 v[94:95], v153 offset:16192
	v_mov_b32_e32 v119, v32
	s_waitcnt lgkmcnt(2)
	v_add_f32_e32 v34, v34, v75
	ds_bpermute_b32 v75, v151, v34
	s_waitcnt lgkmcnt(1)
	v_mfma_f32_16x16x32_bf16 v[92:95], v[92:95], v[76:79], v[96:99]
	s_nop 2
	ds_read_b64_tr_b16 v[96:97], v153 offset:13920
	ds_read_b64_tr_b16 v[98:99], v153 offset:16224
	v_cvt_pk_bf16_f32 v68, v35, v68
	v_cvt_pk_bf16_f32 v69, v69, v70
	s_waitcnt lgkmcnt(2)
	v_add_f32_e32 v34, v34, v75
	v_mfma_f32_16x16x32_bf16 v[80:83], v[80:83], v[76:79], v[100:103]
	v_cvt_pk_bf16_f32 v70, v71, v72
	v_cvt_pk_bf16_f32 v71, v73, v74
	v_div_scale_f32 v35, s[16:17], v34, v34, 1.0
	s_waitcnt lgkmcnt(0)
	v_mfma_f32_16x16x32_bf16 v[76:79], v[96:99], v[76:79], v[84:87]
	ds_read_b64_tr_b16 v[74:75], v153 offset:20736
	ds_read_b64_tr_b16 v[72:73], v153 offset:18432
	s_nop 0
	ds_read_b64_tr_b16 v[84:85], v153 offset:18464
	ds_read_b64_tr_b16 v[86:87], v153 offset:20768
	s_movk_i32 s16, 0x300
	s_waitcnt lgkmcnt(2)
	v_mfma_f32_16x16x32_bf16 v[72:75], v[72:75], v[68:71], v[80:83]
	s_waitcnt lgkmcnt(0)
	v_mfma_f32_16x16x32_bf16 v[80:83], v[84:87], v[68:71], v[88:91]
	ds_read_b64_tr_b16 v[84:85], v153 offset:18496
	ds_read_b64_tr_b16 v[86:87], v153 offset:20800
	s_nop 0
	ds_read_b64_tr_b16 v[88:89], v153 offset:18528
	ds_read_b64_tr_b16 v[90:91], v153 offset:20832
	s_waitcnt lgkmcnt(2)
	v_mfma_f32_16x16x32_bf16 v[84:87], v[84:87], v[68:71], v[92:95]
	s_waitcnt lgkmcnt(0)
	v_mfma_f32_16x16x32_bf16 v[68:71], v[88:91], v[68:71], v[76:79]
	s_nop 2
	v_rcp_f32_e32 v76, v35
	s_nop 0
	v_fma_f32 v77, -v35, v76, 1.0
	v_fmac_f32_e32 v76, v77, v76
	v_div_scale_f32 v77, vcc, 1.0, v34, 1.0
	v_mul_f32_e32 v78, v77, v76
	v_fma_f32 v79, -v35, v78, v77
	v_fmac_f32_e32 v78, v79, v76
	v_fma_f32 v35, -v35, v78, v77
	v_div_fmas_f32 v35, v35, v76, v78
	v_div_fixup_f32 v78, v35, v34, 1.0
	v_lshl_add_u32 v35, s52, 7, v149
	v_mul_lo_u32 v35, v35, s58
	v_add_u32_e32 v35, s56, v35
	v_mov_b64_e32 v[76:77], s[26:27]
	v_mad_i64_i32 v[76:77], s[16:17], v35, s16, v[76:77]
	v_mul_f32_e32 v72, v78, v72
	v_mul_f32_e32 v73, v78, v73
	v_lshl_add_u64 v[76:77], s[34:35], 1, v[76:77]
	v_cvt_pk_bf16_f32 v72, v72, v73
	v_mul_f32_e32 v73, v78, v74
	v_lshl_add_u64 v[76:77], v[76:77], 0, v[118:119]
	v_mul_f32_e32 v74, v78, v75
	v_cvt_pk_bf16_f32 v73, v73, v74
	s_waitcnt vmcnt(0)
	v_mov_b32_e32 v123, v220
	v_mov_b32_e32 v61, v221
	v_mov_b32_e32 v121, v222
	v_mov_b32_e32 v63, v223
	v_mov_b32_e32 v127, v224
	v_mov_b32_e32 v65, v225
	v_mov_b32_e32 v125, v226
	v_mov_b32_e32 v67, v227
	v_mov_b32_e32 v122, v228
	v_mov_b32_e32 v60, v229
	v_mov_b32_e32 v120, v230
	v_mov_b32_e32 v62, v231
	v_mov_b32_e32 v126, v232
	v_mov_b32_e32 v64, v233
	v_mov_b32_e32 v124, v234
	v_mov_b32_e32 v66, v235
	global_store_dwordx2 v[76:77], v[72:73], off
	v_mul_f32_e32 v72, v78, v80
	v_mul_f32_e32 v73, v78, v81
	v_cvt_pk_bf16_f32 v72, v72, v73
	v_mul_f32_e32 v73, v78, v82
	v_mul_f32_e32 v74, v78, v83
	v_cvt_pk_bf16_f32 v73, v73, v74
	global_store_dwordx2 v[76:77], v[72:73], off offset:32
	v_mul_f32_e32 v72, v78, v84
	v_mul_f32_e32 v73, v78, v85
	v_cvt_pk_bf16_f32 v72, v72, v73
	v_mul_f32_e32 v73, v78, v86
	v_mul_f32_e32 v68, v78, v68
	v_mul_f32_e32 v69, v78, v69
	s_cselect_b64 s[16:17], -1, 0
	v_mul_f32_e32 v74, v78, v87
	v_cvt_pk_bf16_f32 v73, v73, v74
	global_store_dwordx2 v[76:77], v[72:73], off offset:64
	v_cvt_pk_bf16_f32 v68, v68, v69
	v_mul_f32_e32 v69, v78, v70
	s_and_b64 s[74:75], s[82:83], s[16:17]
	v_mul_f32_e32 v70, v78, v71
	v_cvt_pk_bf16_f32 v69, v69, v70
	global_store_dwordx2 v[76:77], v[68:69], off offset:96
	s_and_saveexec_b64 s[16:17], s[74:75]
	s_cbranch_execz .LBB0_221
	v_log_f32_e32 v68, v34
	s_ashr_i32 s37, s36, 31
	v_mad_i64_i32 v[34:35], s[74:75], v35, 24, s[24:25]
	v_add_f32_e32 v33, v33, v68
	v_mul_f32_e32 v33, 0x3f317218, v33
	v_lshl_add_u64 v[34:35], s[36:37], 2, v[34:35]
	global_store_dword v[34:35], v33, off

; __device__ __forceinline__ void attn_prefetch(AttnPre& P, const bf16_t* proj, const float* cosT, const float* sinT, const AttnJob& J, int tid) {
;     const int c = tid & 7, i0 = tid >> 3, idxq0 = J.blk * 128, idxk0 = idxq0 - 144;
; #pragma unroll
;     for (int it = 0; it < 2; ++it) { const int tok = J.r + J.dil * (idxq0 + i0 + 64 * it); P.q[it] = *(const u32x4*)(proj + (size_t)tok * LDP + J.qcol + 8 * c); }
; #pragma unroll
;     for (int it = 0; it < 5; ++it) { const int i = i0 + 64 * it, idx = idxk0 + i, tok = J.r + J.dil * idx; P.k[it] = (u32x4){0u, 0u, 0u, 0u}; P.v[it] = (u32x4){0u, 0u, 0u, 0u};
;         if (i < ANR && idx >= 0) { const bf16_t* rp = proj + (size_t)tok * LDP + 8 * c; P.k[it] = *(const u32x4*)(rp + J.kcol); P.v[it] = *(const u32x4*)(rp + J.vcol); } }
.LBB0_250:
	s_or_b64 exec, exec, s[26:27]
	v_readlane_b32 s26, v253, 5
	s_add_i32 s33, s22, s26
	s_cmpk_lt_i32 s33, 0x800
	s_waitcnt lgkmcnt(0)
	s_barrier
	s_cselect_b64 s[30:31], -1, 0
	s_cmpk_gt_i32 s33, 0x7ff
	s_cselect_b64 s[28:29], -1, 0
	s_and_b64 vcc, exec, s[28:29]
	s_mov_b32 s91, s20
	v_mov_b32_e32 v33, v136
	s_mov_b32 s34, s24
	v_readlane_b32 s27, v253, 6
	s_cbranch_vccnz .LBB0_266
	s_ashr_i32 s25, s33, 9
	s_lshl_b32 s26, s25, 2
	s_and_b32 s27, s33, 3
	s_or_b32 s88, s26, s27
	s_lshl_b32 s26, s88, 6
	s_lshl_b32 s25, s25, 6
	s_ashr_i32 s89, s88, 31
	s_bfe_u32 s91, s33, 0x70002
	s_add_i32 s34, s26, 0xd80
	s_add_i32 s36, s25, 0x1180
	s_add_i32 s26, s25, 0x1280
	s_lshl_b64 s[88:89], s[88:89], 2
	s_add_u32 s88, s0, s88
	s_addc_u32 s89, s90, s89
	s_lshl_b32 s25, s91, 7
	v_add_u32_e32 v12, s25, v130
	v_mov_b64_e32 v[8:9], s[40:41]
	global_load_dword v236, v32, s[88:89]
	v_mad_i64_i32 v[10:11], s[88:89], v12, s23, v[8:9]
	s_ashr_i32 s35, s34, 31
	v_add_u32_e32 v12, 64, v12
	s_lshl_b64 s[88:89], s[34:35], 1
	v_mad_i64_i32 v[8:9], s[92:93], v12, s23, v[8:9]
	v_lshl_add_u64 v[10:11], v[10:11], 0, s[88:89]
	v_mov_b32_e32 v113, v32
	v_lshl_add_u64 v[8:9], v[8:9], 0, s[88:89]
	v_lshl_add_u64 v[10:11], v[10:11], 0, v[112:113]
	v_lshl_add_u64 v[12:13], v[8:9], 0, v[112:113]
	global_load_dwordx4 v[8:11], v[10:11], off
	s_nop 0
	global_load_dwordx4 v[12:15], v[12:13], off
	s_add_i32 s35, s25, 0xffffff70
	v_add_u32_e32 v28, s35, v130
	v_mov_b32_e32 v18, v32
	v_mov_b32_e32 v19, v32
	v_cmp_lt_i32_e32 vcc, -1, v28
	v_mov_b32_e32 v16, v32
	v_mov_b32_e32 v17, v32
	v_mov_b64_e32 v[26:27], v[18:19]
	v_mov_b64_e32 v[22:23], v[18:19]
	s_and_b64 s[92:93], s[4:5], vcc
	v_mov_b64_e32 v[24:25], v[16:17]
	v_mov_b64_e32 v[20:21], v[16:17]
	s_and_saveexec_b64 s[88:89], s[92:93]
	s_cbranch_execz .LBB0_253
	v_mad_u64_u32 v[20:21], s[92:93], v28, s23, v[114:115]
	s_ashr_i32 s37, s36, 31
	s_ashr_i32 s27, s26, 31
	v_lshl_add_u64 v[22:23], s[36:37], 1, v[20:21]
	v_lshl_add_u64 v[24:25], s[26:27], 1, v[20:21]
	global_load_dwordx4 v[20:23], v[22:23], off
	s_nop 0
	global_load_dwordx4 v[24:27], v[24:25], off

; __device__ __forceinline__ void attn_prefetch(AttnPre& P, const bf16_t* proj, const float* cosT, const float* sinT, const AttnJob& J, int tid) {
;     ...
;     for (int it = 0; it < 5; ++it) { const int i = i0 + 64 * it, idx = idxk0 + i, tok = J.r + J.dil * idx; P.k[it] = (u32x4){0u, 0u, 0u, 0u}; P.v[it] = (u32x4){0u, 0u, 0u, 0u};
;         if (i < ANR && idx >= 0) { const bf16_t* rp = proj + (size_t)tok * LDP + 8 * c; P.k[it] = *(const u32x4*)(rp + J.kcol); P.v[it] = *(const u32x4*)(rp + J.vcol); } }
;     P.cs[0] = P.cs[1] = (f32x4){1.f, 1.f, 1.f, 1.f}; P.sn[0] = P.sn[1] = (f32x4){0.f, 0.f, 0.f, 0.f};
;     if (tid < 128 + ANR) { const int idx = tid < 128 ? idxq0 + tid : idxk0 + tid - 128;
;         if (idx >= 0) { const int tok = J.r + J.dil * idx; P.cs[0] = *(const f32x4*)(cosT + tok * 8); P.cs[1] = *(const f32x4*)(cosT + tok * 8 + 4); P.sn[0] = *(const f32x4*)(sinT + tok * 8); P.sn[1] = *(const f32x4*)(sinT + tok * 8 + 4); } }
.LBB0_261:
	s_or_b64 exec, exec, s[88:89]
	v_mov_b32_e32 v220, 1.0
	v_mov_b32_e32 v221, 1.0
	v_mov_b32_e32 v222, 1.0
	v_mov_b32_e32 v223, 1.0
	v_mov_b32_e32 v224, 1.0
	v_mov_b32_e32 v225, 1.0
	v_mov_b32_e32 v226, 1.0
	v_mov_b32_e32 v227, 1.0
	v_mov_b32_e32 v228, 0
	v_mov_b32_e32 v229, 0
	v_mov_b32_e32 v230, 0
	v_mov_b32_e32 v231, 0
	v_mov_b32_e32 v232, 0
	v_mov_b32_e32 v233, 0
	v_mov_b32_e32 v234, 0
	v_mov_b32_e32 v235, 0
	s_and_saveexec_b64 s[26:27], s[14:15]
	s_cbranch_execz .LBB0_265
	v_add_u32_e32 v33, s25, v128
	v_add_u32_e32 v34, s35, v133
	v_cndmask_b32_e64 v33, v34, v33, s[16:17]
	v_cmp_lt_i32_e32 vcc, -1, v33
	s_and_saveexec_b64 s[36:37], vcc
	s_cbranch_execz .LBB0_264
	v_lshlrev_b32_e32 v34, 3, v33
	v_mov_b32_e32 v35, v32
	v_readlane_b32 s88, v252, 40
	v_lshlrev_b64 v[34:35], 2, v[34:35]
	v_readlane_b32 s89, v252, 41
	s_nop 1
	v_lshl_add_u64 v[64:65], s[88:89], 0, v[34:35]
	v_readlane_b32 s88, v252, 44
	v_readlane_b32 s89, v252, 45
	global_load_dwordx4 v[220:223], v[64:65], off
	s_nop 0
	global_load_dwordx4 v[224:227], v[64:65], off offset:16
	v_lshl_add_u64 v[34:35], s[88:89], 0, v[34:35]
	global_load_dwordx4 v[228:231], v[34:35], off
	global_load_dwordx4 v[232:235], v[34:35], off offset:16

; #define LAS __attribute__((address_space(3)))
; __device__ __forceinline__ f32x4 mfma16(bf16x8 a, bf16x8 b, f32x4 c) { return __builtin_amdgcn_mfma_f32_16x16x32_bf16(a, b, c, 0, 0, 0); }
; __device__ __forceinline__ void attn_compute(LAS unsigned char* lds, const AttnJob& J, int tid) {
;     ...
;     for (int kk = 0; kk < 2; ++kk) qf[kk] = *(const LAS bf16x8*)(Qs + (16 * w + l15) * AQP + kk * 32 + quad * 8);
;     f32x4 st[10];
;     st[0] = (f32x4){0.f, 0.f, 0.f, 0.f};
; #pragma unroll
;     for (int t = 1; t < 10; ++t) { const LAS bf16_t* kp = Ks + (16 * w + 16 * t + l15) * AQP + quad * 8;
;         const bf16x8 a0 = *(const LAS bf16x8*)kp, a1 = *(const LAS bf16x8*)(kp + 32);
;         f32x4 z = (f32x4){0.f, 0.f, 0.f, 0.f}; z = mfma16(a0, qf[0], z); st[t] = mfma16(a1, qf[1], z); }
;     const int dbase = 144 + l15 - quad * 4;
;     if (J.blk != 0) {
; #pragma unroll
;         for (int j = 0; j < 4; ++j) { if (dbase - 16 - j > J.maxdist) st[1][j] = NEG_BIG; if (dbase - 144 - j < 0) st[9][j] = NEG_BIG; }
.LBB0_265:
	s_or_b64 exec, exec, s[26:27]
.LBB0_266:
	ds_read_b128 v[68:71], v156 offset:18432
	ds_read_b128 v[92:95], v155
	ds_read_b128 v[72:75], v157 offset:18432
	ds_read_b128 v[76:79], v156 offset:18496
	ds_read_b128 v[100:103], v155 offset:64
	s_mov_b32 s25, 0xf149f2ca
	s_waitcnt lgkmcnt(3)
	v_mfma_f32_16x16x32_bf16 v[68:71], v[68:71], v[92:95], 0
	s_cmp_eq_u32 s20, 0
	v_mov_b32_e32 v34, s25
	ds_read_b128 v[108:111], v171 offset:18496
	s_waitcnt lgkmcnt(1)
	v_mfma_f32_16x16x32_bf16 v[104:107], v[76:79], v[100:103], v[68:71]
	s_nop 2
	ds_read_b128 v[68:71], v157 offset:18496
	v_mfma_f32_16x16x32_bf16 v[72:75], v[72:75], v[92:95], 0
	s_waitcnt lgkmcnt(0)
	v_mfma_f32_16x16x32_bf16 v[96:99], v[68:71], v[100:103], v[72:75]
	ds_read_b128 v[68:71], v158 offset:18432
	s_nop 4
	ds_read_b128 v[72:75], v158 offset:18496
	s_waitcnt lgkmcnt(1)
	v_mfma_f32_16x16x32_bf16 v[68:71], v[68:71], v[92:95], 0
	s_waitcnt lgkmcnt(0)
	v_mfma_f32_16x16x32_bf16 v[88:91], v[72:75], v[100:103], v[68:71]
	ds_read_b128 v[72:75], v159 offset:18496
	s_nop 4
	ds_read_b128 v[68:71], v159 offset:18432
	s_waitcnt lgkmcnt(0)
	v_mfma_f32_16x16x32_bf16 v[68:71], v[68:71], v[92:95], 0
	v_mfma_f32_16x16x32_bf16 v[84:87], v[72:75], v[100:103], v[68:71]
	ds_read_b128 v[72:75], v160 offset:18496
	s_nop 5
	ds_read_b128 v[68:71], v160 offset:18432
	s_waitcnt lgkmcnt(0)
	v_mfma_f32_16x16x32_bf16 v[68:71], v[68:71], v[92:95], 0
	v_mfma_f32_16x16x32_bf16 v[80:83], v[72:75], v[100:103], v[68:71]
	ds_read_b128 v[72:75], v161 offset:18496
	s_nop 5
	ds_read_b128 v[68:71], v161 offset:18432
	s_waitcnt lgkmcnt(0)
	v_mfma_f32_16x16x32_bf16 v[68:71], v[68:71], v[92:95], 0
	v_mfma_f32_16x16x32_bf16 v[76:79], v[72:75], v[100:103], v[68:71]
	ds_read_b128 v[72:75], v163 offset:18496
	s_nop 5
	ds_read_b128 v[68:71], v163 offset:18432
	s_waitcnt lgkmcnt(0)
	v_mfma_f32_16x16x32_bf16 v[68:71], v[68:71], v[92:95], 0
	v_mfma_f32_16x16x32_bf16 v[68:71], v[72:75], v[100:103], v[68:71]
	ds_read_b128 v[72:75], v171 offset:18432
	s_waitcnt lgkmcnt(0)
	v_mfma_f32_16x16x32_bf16 v[72:75], v[72:75], v[92:95], 0
	v_mfma_f32_16x16x32_bf16 v[72:75], v[108:111], v[100:103], v[72:75]
	ds_read_b128 v[108:111], v180 offset:18432
	s_waitcnt lgkmcnt(0)
	v_mfma_f32_16x16x32_bf16 v[92:95], v[108:111], v[92:95], 0
	ds_read_b128 v[108:111], v180 offset:18496
	s_waitcnt lgkmcnt(0)
	v_mfma_f32_16x16x32_bf16 v[108:111], v[108:111], v[100:103], v[92:95]
	s_cbranch_scc1 .LBB0_275
	v_cndmask_b32_e64 v100, v104, v34, s[42:43]
	v_cndmask_b32_e64 v101, v105, v208, s[44:45]
	v_cndmask_b32_e64 v102, v106, v208, s[46:47]
	v_cndmask_b32_e64 v103, v107, v208, s[50:51]
	s_nop 2
	v_cndmask_b32_e64 v95, v111, v208, s[48:49]
	v_cndmask_b32_e64 v94, v110, v208, s[82:83]
	v_cndmask_b32_e64 v93, v109, v208, s[84:85]
	v_cndmask_b32_e64 v92, v108, v208, s[86:87]
	s_cbranch_execnz .LBB0_269

; __device__ __forceinline__ void attn_compute(LAS unsigned char* lds, const AttnJob& J, int tid) {
;     ...
;     float mx = NEG_BIG;
; #pragma unroll
;     for (int t = 1; t < 10; ++t) mx = fmaxf(mx, fmaxf(fmaxf(st[t][0], st[t][1]), fmaxf(st[t][2], st[t][3])));
;     mx = fmaxf(mx, __shfl_xor(mx, 16)); mx = fmaxf(mx, __shfl_xor(mx, 32));
;     if (J.has_sink) mx = fmaxf(mx, J.sink);
;     float den = 0.f;
; #pragma unroll
;     for (int t = 1; t < 10; ++t)
; #pragma unroll
;         for (int j = 0; j < 4; ++j) { const float p = __builtin_amdgcn_exp2f(st[t][j] - mx); st[t][j] = p; den += p; }
;     den += __shfl_xor(den, 16); den += __shfl_xor(den, 32);
;     if (J.has_sink) den += __builtin_amdgcn_exp2f(J.sink - mx);
.LBB0_269:
	v_max_f32_e32 v34, v101, v101
	v_max_f32_e32 v35, v100, v100
	v_max_f32_e32 v34, v35, v34
	v_max_f32_e32 v35, v103, v103
	v_max_f32_e32 v104, v102, v102
	v_max_f32_e32 v35, v104, v35
	v_max3_f32 v34, v34, v35, s25
	v_max_f32_e32 v35, v99, v99
	v_max_f32_e32 v104, v98, v98
	v_max_f32_e32 v35, v104, v35
	v_max_f32_e32 v104, v91, v91
	v_max_f32_e32 v105, v90, v90
	v_max_f32_e32 v104, v105, v104
	v_max3_f32 v35, v96, v97, v35
	v_max3_f32 v104, v88, v89, v104
	v_max3_f32 v34, v34, v35, v104
	v_max_f32_e32 v35, v87, v87
	v_max_f32_e32 v104, v86, v86
	v_max_f32_e32 v35, v104, v35
	v_max_f32_e32 v104, v83, v83
	v_max_f32_e32 v105, v82, v82
	v_max_f32_e32 v104, v105, v104
	v_max3_f32 v35, v84, v85, v35
	v_max3_f32 v104, v80, v81, v104
	v_max3_f32 v34, v34, v35, v104
	v_max_f32_e32 v35, v79, v79
	v_max_f32_e32 v104, v78, v78
	v_max_f32_e32 v35, v104, v35
	v_max_f32_e32 v104, v71, v71
	v_max_f32_e32 v105, v70, v70
	v_max_f32_e32 v104, v105, v104
	v_max3_f32 v35, v76, v77, v35
	v_max3_f32 v104, v68, v69, v104
	v_max3_f32 v34, v34, v35, v104
	v_max_f32_e32 v35, v75, v75
	v_max_f32_e32 v104, v74, v74
	v_max_f32_e32 v35, v104, v35
	v_max_f32_e32 v104, v95, v95
	v_max_f32_e32 v105, v94, v94
	v_max_f32_e32 v104, v105, v104
	v_max3_f32 v35, v72, v73, v35
	v_max3_f32 v104, v92, v93, v104
	v_max3_f32 v34, v34, v35, v104
	ds_bpermute_b32 v35, v149, v34
	s_ashr_i32 s25, s24, 31
	s_waitcnt lgkmcnt(0)
	v_max_f32_e32 v35, v35, v35
	v_max_f32_e32 v34, v34, v35
	ds_bpermute_b32 v35, v150, v34
	s_waitcnt lgkmcnt(0)
	v_max3_f32 v34, v34, v35, v136
	v_sub_f32_e32 v35, v100, v34
	v_exp_f32_e32 v100, v35
	v_sub_f32_e32 v101, v101, v34
	v_exp_f32_e32 v101, v101
	v_sub_f32_e32 v102, v102, v34
	v_exp_f32_e32 v102, v102
	v_sub_f32_e32 v103, v103, v34
	v_exp_f32_e32 v103, v103
	v_sub_f32_e32 v96, v96, v34
	v_add_f32_e32 v35, 0, v100
	v_exp_f32_e32 v96, v96
	v_sub_f32_e32 v97, v97, v34
	v_add_f32_e32 v35, v101, v35
	v_exp_f32_e32 v97, v97
	v_sub_f32_e32 v98, v98, v34
	v_add_f32_e32 v35, v102, v35
	v_exp_f32_e32 v110, v98
	v_sub_f32_e32 v98, v99, v34
	v_add_f32_e32 v35, v103, v35
	v_exp_f32_e32 v111, v98
	v_sub_f32_e32 v88, v88, v34
	v_add_f32_e32 v35, v96, v35
	v_exp_f32_e32 v113, v88
	v_sub_f32_e32 v88, v89, v34
	v_add_f32_e32 v35, v97, v35
	v_exp_f32_e32 v117, v88
	v_sub_f32_e32 v88, v90, v34
	v_add_f32_e32 v35, v110, v35
	v_exp_f32_e32 v164, v88
	v_sub_f32_e32 v88, v91, v34
	v_add_f32_e32 v35, v111, v35
	v_exp_f32_e32 v165, v88
	v_sub_f32_e32 v84, v84, v34
	v_add_f32_e32 v35, v113, v35
	v_exp_f32_e32 v84, v84
	v_sub_f32_e32 v85, v85, v34
	v_add_f32_e32 v35, v117, v35
	v_exp_f32_e32 v85, v85
	v_sub_f32_e32 v86, v86, v34
	v_add_f32_e32 v35, v164, v35
	v_exp_f32_e32 v86, v86
	v_sub_f32_e32 v87, v87, v34
	v_add_f32_e32 v35, v165, v35
	v_exp_f32_e32 v87, v87
	v_sub_f32_e32 v80, v80, v34
	v_add_f32_e32 v35, v84, v35
	v_exp_f32_e32 v166, v80
	v_sub_f32_e32 v80, v81, v34
	v_add_f32_e32 v35, v85, v35
	v_exp_f32_e32 v167, v80
	v_sub_f32_e32 v80, v82, v34
	v_add_f32_e32 v35, v86, v35
	v_exp_f32_e32 v181, v80
	v_sub_f32_e32 v80, v83, v34
	v_add_f32_e32 v35, v87, v35
	v_exp_f32_e32 v190, v80
	v_sub_f32_e32 v76, v76, v34
	v_add_f32_e32 v35, v166, v35
	v_exp_f32_e32 v76, v76
	v_sub_f32_e32 v77, v77, v34
	v_add_f32_e32 v35, v167, v35
	v_exp_f32_e32 v77, v77
	v_sub_f32_e32 v78, v78, v34
	v_add_f32_e32 v35, v181, v35
	v_exp_f32_e32 v78, v78
	v_sub_f32_e32 v79, v79, v34
	v_add_f32_e32 v35, v190, v35
	v_exp_f32_e32 v79, v79
	v_sub_f32_e32 v68, v68, v34
	v_add_f32_e32 v35, v76, v35
	v_exp_f32_e32 v80, v68
	v_sub_f32_e32 v68, v69, v34
	v_add_f32_e32 v35, v77, v35
	v_exp_f32_e32 v81, v68
	v_sub_f32_e32 v68, v70, v34
	v_add_f32_e32 v35, v78, v35
	v_exp_f32_e32 v82, v68
	v_sub_f32_e32 v68, v71, v34
	v_add_f32_e32 v35, v79, v35
	v_exp_f32_e32 v83, v68
	v_add_f32_e32 v35, v80, v35
	v_add_f32_e32 v35, v81, v35
	v_add_f32_e32 v35, v82, v35
	v_add_f32_e32 v68, v83, v35
	v_sub_f32_e32 v35, v72, v34
	v_exp_f32_e32 v35, v35
	s_nop 0
	v_add_f32_e32 v69, v35, v68
	v_sub_f32_e32 v68, v73, v34
	v_exp_f32_e32 v68, v68
	s_nop 0
	v_add_f32_e32 v70, v68, v69
	v_sub_f32_e32 v69, v74, v34
	v_exp_f32_e32 v69, v69
	s_nop 0
	v_add_f32_e32 v71, v69, v70
	v_sub_f32_e32 v70, v75, v34
	v_exp_f32_e32 v70, v70
	s_nop 0
	v_add_f32_e32 v72, v70, v71
	v_sub_f32_e32 v71, v92, v34
	v_exp_f32_e32 v71, v71
	s_nop 0
	v_add_f32_e32 v73, v71, v72
	v_sub_f32_e32 v72, v93, v34
	v_exp_f32_e32 v72, v72
	s_nop 0
	v_add_f32_e32 v74, v72, v73
	v_sub_f32_e32 v73, v94, v34
	v_exp_f32_e32 v73, v73
	s_nop 0
	v_add_f32_e32 v75, v73, v74
	v_sub_f32_e32 v74, v95, v34
	v_exp_f32_e32 v74, v74
	v_sub_f32_e32 v34, v136, v34
	v_exp_f32_e32 v34, v34
	v_add_f32_e32 v75, v74, v75
	ds_bpermute_b32 v88, v149, v75
	s_waitcnt lgkmcnt(0)
	v_add_f32_e32 v75, v75, v88
	ds_bpermute_b32 v88, v150, v75
	s_waitcnt lgkmcnt(0)
	v_add_f32_e32 v75, v75, v88
	v_cvt_pk_bf16_f32 v88, v32, v32
	v_cvt_pk_bf16_f32 v89, v32, v32
	v_cvt_pk_bf16_f32 v90, v100, v101
	v_cvt_pk_bf16_f32 v91, v102, v103
	ds_read_b64_tr_b16 v[94:95], v151 offset:59904
	ds_read_b64_tr_b16 v[92:93], v151 offset:57600
	ds_read_b64_tr_b16 v[98:99], v151 offset:57632
	ds_read_b64_tr_b16 v[100:101], v151 offset:59936
	ds_read_b64_tr_b16 v[102:103], v151 offset:57664
	ds_read_b64_tr_b16 v[104:105], v151 offset:59968
	ds_read_b64_tr_b16 v[106:107], v151 offset:57696
	ds_read_b64_tr_b16 v[108:109], v151 offset:60000
	s_waitcnt lgkmcnt(6)
	v_mfma_f32_16x16x32_bf16 v[92:95], v[92:95], v[88:91], 0
	v_add_f32_e32 v34, v34, v75
	s_waitcnt lgkmcnt(4)
	v_mfma_f32_16x16x32_bf16 v[98:101], v[98:101], v[88:91], 0
	s_waitcnt lgkmcnt(2)
	v_mfma_f32_16x16x32_bf16 v[102:105], v[102:105], v[88:91], 0
	s_waitcnt lgkmcnt(0)
; __device__ __forceinline__ unsigned cvt_pk_bf16(float lo, float hi) { unsigned r; asm volatile("v_cvt_pk_bf16_f32 %0, %1, %2" : "=v"(r) : "v"(lo), "v"(hi)); return r; }
; #define LAS __attribute__((address_space(3)))
; __device__ __forceinline__ f32x4 mfma16(bf16x8 a, bf16x8 b, f32x4 c) { return __builtin_amdgcn_mfma_f32_16x16x32_bf16(a, b, c, 0, 0, 0); }
; __device__ __forceinline__ bf16x8 cat44(s16x4 lo, s16x4 hi) { return __builtin_shufflevector(lo, hi, 0, 1, 2, 3, 4, 5, 6, 7); }
; __device__ __forceinline__ s16x4 lds_tr(const LAS bf16_t* p) { return __builtin_bit_cast(s16x4, __builtin_amdgcn_ds_read_tr16_b64_v4i16((LAS v4i16_t*)p)); }
; __device__ __forceinline__ void attn_compute(LAS unsigned char* lds, const AttnJob& J, int tid) {
;     ...
;     f32x4 o[4];
; #pragma unroll
;     for (int dt = 0; dt < 4; ++dt) o[dt] = (f32x4){0.f, 0.f, 0.f, 0.f};
; #pragma unroll
;     for (int ks = 0; ks < 5; ++ks) {
;         u32x4 pw; pw.x = cvt_pk_bf16(st[2 * ks][0], st[2 * ks][1]); pw.y = cvt_pk_bf16(st[2 * ks][2], st[2 * ks][3]); pw.z = cvt_pk_bf16(st[2 * ks + 1][0], st[2 * ks + 1][1]); pw.w = cvt_pk_bf16(st[2 * ks + 1][2], st[2 * ks + 1][3]);
;         const bf16x8 pb = __builtin_bit_cast(bf16x8, pw);
; #pragma unroll
;         for (int dt = 0; dt < 4; ++dt) { const LAS bf16_t* vp = Vs + (16 * w + 32 * ks + quad * 4 + (l15 >> 2)) * AQP + 16 * dt + 4 * (l15 & 3);
;             const s16x4 lo = lds_tr(vp), hi = lds_tr(vp + 16 * AQP);
;             o[dt] = mfma16(cat44(lo, hi), pb, o[dt]); }
;     }
;     const float inv = 1.0f / den;
;     const int tokq = J.r + J.dil * (idxq0 + 16 * w + l15);
;     bf16_t* op = J.out + (size_t)tokq * J.out_ld + J.out_col + quad * 4;
; #pragma unroll
;     for (int dt = 0; dt < 4; ++dt) { u32x2 wv; wv.x = cvt_pk_bf16(o[dt][0] * inv, o[dt][1] * inv); wv.y = cvt_pk_bf16(o[dt][2] * inv, o[dt][3] * inv); *(u32x2*)(op + 16 * dt) = wv; }
	v_mfma_f32_16x16x32_bf16 v[88:91], v[106:109], v[88:91], 0
	v_cvt_pk_bf16_f32 v106, v96, v97
	v_cvt_pk_bf16_f32 v107, v110, v111
	v_cvt_pk_bf16_f32 v108, v113, v117
	v_cvt_pk_bf16_f32 v109, v164, v165
	ds_read_b64_tr_b16 v[184:185], v151 offset:64512
	ds_read_b64_tr_b16 v[182:183], v151 offset:62208
	ds_read_b64_tr_b16 v[186:187], v151 offset:62240
	ds_read_b64_tr_b16 v[188:189], v151 offset:64544
	s_waitcnt lgkmcnt(2)
	v_mfma_f32_16x16x32_bf16 v[92:95], v[182:185], v[106:109], v[92:95]
	ds_read_b64_tr_b16 v[182:183], v151 offset:62272
	ds_read_b64_tr_b16 v[184:185], v151 offset:64576
	v_mov_b32_e32 v117, v32
	s_waitcnt lgkmcnt(2)
	v_mfma_f32_16x16x32_bf16 v[96:99], v[186:189], v[106:109], v[98:101]
	s_waitcnt lgkmcnt(0)
	v_mfma_f32_16x16x32_bf16 v[100:103], v[182:185], v[106:109], v[102:105]
	ds_read_b64_tr_b16 v[182:183], v151 offset:62304
	ds_read_b64_tr_b16 v[184:185], v151 offset:64608
	v_cvt_pk_bf16_f32 v84, v84, v85
	v_cvt_pk_bf16_f32 v85, v86, v87
	s_waitcnt lgkmcnt(0)
	v_mfma_f32_16x16x32_bf16 v[88:91], v[182:185], v[106:109], v[88:91]
	v_cvt_pk_bf16_f32 v86, v166, v167
	v_cvt_pk_bf16_f32 v87, v181, v190
	ds_read_b64_tr_b16 v[106:107], v152 offset:11520
	ds_read_b64_tr_b16 v[104:105], v152 offset:9216
	ds_read_b64_tr_b16 v[108:109], v152 offset:9248
	s_waitcnt lgkmcnt(1)
	v_mfma_f32_16x16x32_bf16 v[92:95], v[104:107], v[84:87], v[92:95]
	ds_read_b64_tr_b16 v[110:111], v152 offset:11552
	ds_read_b64_tr_b16 v[104:105], v152 offset:9280
	ds_read_b64_tr_b16 v[106:107], v152 offset:11584
	s_waitcnt lgkmcnt(0)
	v_mfma_f32_16x16x32_bf16 v[100:103], v[104:107], v[84:87], v[100:103]
	ds_read_b64_tr_b16 v[104:105], v152 offset:9312
	ds_read_b64_tr_b16 v[106:107], v152 offset:11616
	v_cvt_pk_bf16_f32 v76, v76, v77
	v_cvt_pk_bf16_f32 v77, v78, v79
	v_mfma_f32_16x16x32_bf16 v[96:99], v[108:111], v[84:87], v[96:99]
	v_cvt_pk_bf16_f32 v78, v80, v81
	v_cvt_pk_bf16_f32 v79, v82, v83
	s_waitcnt lgkmcnt(0)
	v_mfma_f32_16x16x32_bf16 v[84:87], v[104:107], v[84:87], v[88:91]
	ds_read_b64_tr_b16 v[82:83], v152 offset:16128
	ds_read_b64_tr_b16 v[80:81], v152 offset:13824
	s_nop 0
	ds_read_b64_tr_b16 v[88:89], v152 offset:13856
	ds_read_b64_tr_b16 v[90:91], v152 offset:16160
	s_waitcnt lgkmcnt(2)
	v_mfma_f32_16x16x32_bf16 v[80:83], v[80:83], v[76:79], v[92:95]
	s_nop 2
	ds_read_b64_tr_b16 v[92:93], v152 offset:13888
	ds_read_b64_tr_b16 v[94:95], v152 offset:16192
	s_waitcnt lgkmcnt(2)
	v_mfma_f32_16x16x32_bf16 v[88:91], v[88:91], v[76:79], v[96:99]
	s_nop 2
	ds_read_b64_tr_b16 v[96:97], v152 offset:13920
	ds_read_b64_tr_b16 v[98:99], v152 offset:16224
	v_cvt_pk_bf16_f32 v68, v35, v68
	v_cvt_pk_bf16_f32 v69, v69, v70
	s_waitcnt lgkmcnt(2)
	v_mfma_f32_16x16x32_bf16 v[92:95], v[92:95], v[76:79], v[100:103]
	v_cvt_pk_bf16_f32 v70, v71, v72
	v_cvt_pk_bf16_f32 v71, v73, v74
	v_div_scale_f32 v35, s[26:27], v34, v34, 1.0
	s_waitcnt lgkmcnt(0)
	v_mfma_f32_16x16x32_bf16 v[76:79], v[96:99], v[76:79], v[84:87]
	ds_read_b64_tr_b16 v[74:75], v152 offset:20736
	ds_read_b64_tr_b16 v[72:73], v152 offset:18432
	s_nop 0
	ds_read_b64_tr_b16 v[84:85], v152 offset:18464
	ds_read_b64_tr_b16 v[86:87], v152 offset:20768
	s_waitcnt lgkmcnt(2)
	v_mfma_f32_16x16x32_bf16 v[72:75], v[72:75], v[68:71], v[80:83]
	s_waitcnt lgkmcnt(0)
	v_mfma_f32_16x16x32_bf16 v[80:83], v[84:87], v[68:71], v[88:91]
	ds_read_b64_tr_b16 v[84:85], v152 offset:18496
	ds_read_b64_tr_b16 v[86:87], v152 offset:20800
	s_nop 0
	ds_read_b64_tr_b16 v[88:89], v152 offset:18528
	ds_read_b64_tr_b16 v[90:91], v152 offset:20832
	s_waitcnt lgkmcnt(2)
	v_mfma_f32_16x16x32_bf16 v[84:87], v[84:87], v[68:71], v[92:95]
	s_waitcnt lgkmcnt(0)
	v_mfma_f32_16x16x32_bf16 v[68:71], v[88:91], v[68:71], v[76:79]
	s_nop 2
	v_rcp_f32_e32 v76, v35
	s_nop 0
	v_fma_f32 v77, -v35, v76, 1.0
	v_fmac_f32_e32 v76, v77, v76
	v_div_scale_f32 v77, vcc, 1.0, v34, 1.0
	v_mul_f32_e32 v78, v77, v76
	v_fma_f32 v79, -v35, v78, v77
	v_fmac_f32_e32 v78, v79, v76
	v_fma_f32 v35, -v35, v78, v77
	v_div_fmas_f32 v35, v35, v76, v78
	v_div_fixup_f32 v76, v35, v34, 1.0
	v_lshl_add_u32 v77, s20, 7, v148
	v_mov_b64_e32 v[34:35], s[40:41]
	v_mad_i64_i32 v[34:35], s[26:27], v77, s23, v[34:35]
	v_mul_f32_e32 v72, v76, v72
	v_mul_f32_e32 v73, v76, v73
	v_lshl_add_u64 v[34:35], s[24:25], 1, v[34:35]
	v_cvt_pk_bf16_f32 v72, v72, v73
	v_mul_f32_e32 v73, v76, v74
	v_lshl_add_u64 v[34:35], v[34:35], 0, v[116:117]
	v_mul_f32_e32 v74, v76, v75
	v_cvt_pk_bf16_f32 v73, v73, v74
	s_waitcnt vmcnt(0)
	v_mul_f32_e32 v33, 0x3fb8aa3b, v236
	v_mov_b32_e32 v60, v220
	v_mov_b32_e32 v120, v221
	v_mov_b32_e32 v62, v222
	v_mov_b32_e32 v118, v223
	v_mov_b32_e32 v64, v224
	v_mov_b32_e32 v124, v225
	v_mov_b32_e32 v66, v226
	v_mov_b32_e32 v122, v227
	v_mov_b32_e32 v61, v228
	v_mov_b32_e32 v121, v229
	v_mov_b32_e32 v63, v230
	v_mov_b32_e32 v119, v231
	v_mov_b32_e32 v65, v232
	v_mov_b32_e32 v125, v233
	v_mov_b32_e32 v67, v234
	v_mov_b32_e32 v123, v235
	global_store_dwordx2 v[34:35], v[72:73], off
	v_mul_f32_e32 v72, v76, v80
	v_mul_f32_e32 v73, v76, v81
	v_cvt_pk_bf16_f32 v72, v72, v73
	v_mul_f32_e32 v73, v76, v82
	v_mul_f32_e32 v74, v76, v83
	v_cvt_pk_bf16_f32 v73, v73, v74
	global_store_dwordx2 v[34:35], v[72:73], off offset:32
	v_mul_f32_e32 v72, v76, v84
	v_mul_f32_e32 v73, v76, v85
	v_cvt_pk_bf16_f32 v72, v72, v73
	v_mul_f32_e32 v73, v76, v86
	v_mul_f32_e32 v68, v76, v68
	v_mul_f32_e32 v69, v76, v69
	v_mul_f32_e32 v74, v76, v87
	v_cvt_pk_bf16_f32 v73, v73, v74
	global_store_dwordx2 v[34:35], v[72:73], off offset:64
	v_cvt_pk_bf16_f32 v68, v68, v69
	v_mul_f32_e32 v69, v76, v70
	v_mul_f32_e32 v70, v76, v71
	v_cvt_pk_bf16_f32 v69, v69, v70
	global_store_dwordx2 v[34:35], v[68:69], off offset:96
	s_waitcnt lgkmcnt(0)
	s_barrier
	s_andn2_b64 vcc, exec, s[30:31]
	s_cbranch_vccnz .LBB0_241
	s_mov_b32 s24, s34
	v_mov_b32_e32 v136, v33
	s_mov_b32 s20, s91
	s_mov_b32 s22, s33
	s_branch .LBB0_241
